# mixer loop: next-item prefetch made non-blocking (row-sum loads straight into home registers, conservative waits in the issue block removed); P1 gate rows moved to workgroups 120..255
# speedup vs baseline: 1.0014x; 1.0014x over previous
.LBB0_157:
	s_or_b64 exec, exec, s[2:3]
	s_add_u32 s52, s78, 0xcc0000
	s_addc_u32 s53, s79, 0
	s_sub_i32 s98, 0xff, s96
	s_cmpk_gt_i32 s98, 0x87
	s_cbranch_scc1 .LBB0_163
	s_load_dwordx16 s[36:51], s[0:1], 0x0
	s_load_dword s18, s[0:1], 0xb0
	v_ashrrev_i32_e32 v145, 31, v144
	v_add_u32_e32 v2, 0xfffffe00, v144
	v_lshlrev_b64 v[0:1], 2, v[144:145]
	s_waitcnt lgkmcnt(0)
	s_mov_b64 s[16:17], s[48:49]
	s_add_u32 s2, s16, 0x2000
	s_addc_u32 s3, s17, 0
	s_movk_i32 s19, 0x1ff
	s_mov_b32 s4, s98
	s_branch .LBB0_160

.LBB0_696:
	s_andn2_b64 vcc, exec, s[0:1]
	s_cbranch_vccnz .LBB0_707
	s_ashr_i32 s0, s13, 3
	s_add_i32 s64, s0, -1
	s_add_i32 s0, s0, s13
	s_and_b32 s1, s0, 4
	s_mul_i32 s27, s64, 0x120000
	s_mul_hi_i32 s26, s64, 0x120000
	s_add_u32 s65, s70, s27
	s_addc_u32 s68, s71, s26
	s_lshl_b32 s0, s0, 14
	s_and_b32 s69, s0, 0xc000
	v_lshlrev_b32_e32 v104, 3, v129
	s_cmp_eq_u32 s1, 0
	s_mov_b64 s[38:39], -1
	v_ashrrev_i32_e32 v105, 31, v104
	s_cbranch_scc1 .LBB0_699
	s_lshl_b32 s26, s69, 1
	s_add_u32 s27, s65, s26
	s_addc_u32 s74, s68, 0
	s_add_u32 s0, s27, 0x60000
	s_addc_u32 s1, s74, 0
	s_lshl_b32 s75, s64, 7
	v_add_u32_e32 v2, s75, v133
	v_lshlrev_b64 v[4:5], 1, v[104:105]
	v_ashrrev_i32_e32 v3, 31, v2
	v_lshl_add_u64 v[0:1], s[0:1], 0, v[4:5]
	v_lshl_add_u64 v[6:7], v[2:3], 3, s[72:73]
	global_load_dwordx4 v[0:3], v[0:1], off
	s_nop 0
	global_load_dwordx2 v[148:149], v[6:7], off
	v_lshlrev_b32_e32 v6, 3, v132
	v_ashrrev_i32_e32 v10, 4, v132
	s_add_u32 s38, s21, s26
	v_ashrrev_i32_e32 v7, 31, v6
	v_add_u32_e32 v10, s75, v10
	s_addc_u32 s39, s22, 0
	v_lshlrev_b64 v[8:9], 1, v[6:7]
	v_ashrrev_i32_e32 v11, 31, v10
	v_lshl_add_u64 v[4:5], s[38:39], 0, v[4:5]
	v_lshl_add_u64 v[6:7], s[0:1], 0, v[8:9]
	v_lshl_add_u64 v[10:11], v[10:11], 3, s[72:73]
	v_lshl_add_u64 v[8:9], s[38:39], 0, v[8:9]
	global_load_dwordx4 v[12:15], v[4:5], off
	s_nop 0
	global_load_dwordx4 v[4:7], v[6:7], off
	s_nop 0
	global_load_dwordx2 v[150:151], v[10:11], off
	global_load_dwordx4 v[20:23], v[8:9], off
	v_lshlrev_b32_e32 v8, 3, v131
	v_ashrrev_i32_e32 v10, 4, v131
	v_ashrrev_i32_e32 v9, 31, v8
	v_add_u32_e32 v10, s75, v10
	v_lshlrev_b64 v[16:17], 1, v[8:9]
	v_ashrrev_i32_e32 v11, 31, v10
	v_lshl_add_u64 v[8:9], s[0:1], 0, v[16:17]
	v_lshl_add_u64 v[18:19], v[10:11], 3, s[72:73]
	global_load_dwordx4 v[8:11], v[8:9], off
	s_nop 0
	global_load_dwordx2 v[152:153], v[18:19], off
	v_lshlrev_b32_e32 v18, 3, v130
	v_ashrrev_i32_e32 v28, 4, v130
	v_ashrrev_i32_e32 v19, 31, v18
	v_add_u32_e32 v96, s75, v28
	v_lshlrev_b64 v[30:31], 1, v[18:19]
	v_ashrrev_i32_e32 v97, 31, v96
	v_lshl_add_u64 v[16:17], s[38:39], 0, v[16:17]
	v_lshl_add_u64 v[18:19], s[0:1], 0, v[30:31]
	v_lshl_add_u64 v[96:97], v[96:97], 3, s[72:73]
	global_load_dwordx4 v[24:27], v[16:17], off
	s_nop 0
	global_load_dwordx4 v[16:19], v[18:19], off
	v_lshl_add_u64 v[30:31], s[38:39], 0, v[30:31]
	global_load_dwordx2 v[154:155], v[96:97], off
	s_nop 0
	global_load_dwordx4 v[96:99], v[30:31], off
	s_add_u32 s0, s27, 0x40000
	s_addc_u32 s1, s74, 0
	s_mov_b64 s[38:39], 0
.LBB0_699:
	s_andn2_b64 vcc, exec, s[38:39]
	s_cbranch_vccnz .LBB0_742
	s_lshl_b32 s26, s69, 1
	s_add_u32 s0, s19, s26
	v_add_u32_e32 v2, 0x1000, v104
	v_add_u32_e32 v8, 0x2000, v104
	s_addc_u32 s1, s20, 0
	v_ashrrev_i32_e32 v3, 31, v2
	v_ashrrev_i32_e32 v9, 31, v8
	v_add_u32_e32 v10, 0x3000, v104
	v_lshl_add_u64 v[0:1], v[104:105], 1, s[0:1]
	v_lshl_add_u64 v[4:5], v[2:3], 1, s[0:1]
	v_lshl_add_u64 v[8:9], v[8:9], 1, s[0:1]
	v_ashrrev_i32_e32 v11, 31, v10
	global_load_dwordx4 v[0:3], v[0:1], off
	s_nop 0
	global_load_dwordx4 v[4:7], v[4:5], off
	v_lshl_add_u64 v[12:13], v[10:11], 1, s[0:1]
	global_load_dwordx4 v[8:11], v[8:9], off
	s_nop 0
	global_load_dwordx4 v[16:19], v[12:13], off
	s_add_u32 s38, s65, s26
	s_addc_u32 s39, s68, 0
	s_and_b32 s0, s64, 15
	s_cmp_lg_u32 s0, 0
	s_cselect_b64 s[0:1], -1, 0
	s_add_u32 s64, s38, 0xffee0000
	s_movk_i32 s26, 0xff
	s_addc_u32 s65, s39, -1
	v_cmp_lt_i32_e32 vcc, s26, v129
	s_and_saveexec_b64 s[68:69], vcc
	s_xor_b64 s[68:69], exec, s[68:69]
	s_cbranch_execz .LBB0_704
	v_mov_b32_e32 v28, v29
	v_mov_b32_e32 v30, v29
	v_mov_b32_e32 v31, v29
	v_mov_b64_e32 v[12:13], v[28:29]
	v_cmp_gt_u32_e32 vcc, s33, v129
	v_mov_b64_e32 v[14:15], v[30:31]
	s_and_saveexec_b64 s[74:75], vcc
	s_cbranch_execz .LBB0_703
	v_mov_b32_e32 v105, v29
	v_lshl_add_u64 v[12:13], v[104:105], 1, s[38:39]
	global_load_dwordx4 v[12:15], v[12:13], off offset:-4096

.LBB0_704:
	s_or_saveexec_b64 s[68:69], s[68:69]
	v_cndmask_b32_e64 v20, 0, 1, s[0:1]
	v_cmp_ne_u32_e64 s[0:1], 1, v20
	s_xor_b64 exec, exec, s[68:69]
	s_cbranch_execz .LBB0_709
	s_and_b64 vcc, exec, s[0:1]
	s_cbranch_vccnz .LBB0_708
	v_add_u32_e32 v12, 0x3800, v104
	v_ashrrev_i32_e32 v13, 31, v12
	v_lshl_add_u64 v[12:13], v[12:13], 1, s[64:65]
	global_load_dwordx4 v[12:15], v[12:13], off
	s_branch .LBB0_709

.LBB0_708:
	v_mov_b32_e32 v28, v29
	v_mov_b32_e32 v30, v29
	v_mov_b32_e32 v31, v29
	v_mov_b64_e32 v[12:13], v[28:29]
	v_mov_b64_e32 v[14:15], v[30:31]

.LBB0_713:
	s_andn2_saveexec_b64 s[68:69], s[68:69]
	s_cbranch_execz .LBB0_717
	s_and_b64 vcc, exec, s[0:1]
	s_cbranch_vccnz .LBB0_716
	v_lshl_add_u32 v20, v132, 3, v173
	v_ashrrev_i32_e32 v21, 31, v20
	v_lshl_add_u64 v[20:21], v[20:21], 1, s[64:65]
	global_load_dwordx4 v[20:23], v[20:21], off
	s_branch .LBB0_717
.LBB0_716:
	v_mov_b32_e32 v28, v29
	v_mov_b32_e32 v30, v29
	v_mov_b32_e32 v31, v29
	v_mov_b64_e32 v[20:21], v[28:29]
	v_mov_b64_e32 v[22:23], v[30:31]
.LBB0_717:
	s_or_b64 exec, exec, s[68:69]
	s_movk_i32 s26, 0xfcff
	v_cmp_lt_i32_e32 vcc, s26, v129
	s_and_saveexec_b64 s[68:69], vcc
	s_xor_b64 s[68:69], exec, s[68:69]
	s_cbranch_execz .LBB0_721
	v_mov_b32_e32 v28, v29
	v_mov_b32_e32 v30, v29
	v_mov_b32_e32 v31, v29
	v_mov_b64_e32 v[24:25], v[28:29]
	v_cmp_gt_u32_e32 vcc, s33, v131
	v_mov_b64_e32 v[26:27], v[30:31]
	s_and_saveexec_b64 s[74:75], vcc
	s_cbranch_execz .LBB0_720
	v_lshlrev_b32_e32 v24, 4, v131
	global_load_dwordx4 v[24:27], v24, s[38:39] offset:-4096

.LBB0_721:
	s_andn2_saveexec_b64 s[68:69], s[68:69]
	s_cbranch_execz .LBB0_725
	s_and_b64 vcc, exec, s[0:1]
	s_cbranch_vccnz .LBB0_724
	v_lshl_add_u32 v24, v131, 3, v173
	v_ashrrev_i32_e32 v25, 31, v24
	v_lshl_add_u64 v[24:25], v[24:25], 1, s[64:65]
	global_load_dwordx4 v[24:27], v[24:25], off
	s_branch .LBB0_725
.LBB0_724:
	v_mov_b32_e32 v28, v29
	v_mov_b32_e32 v30, v29
	v_mov_b32_e32 v31, v29
	v_mov_b64_e32 v[24:25], v[28:29]
	v_mov_b64_e32 v[26:27], v[30:31]
.LBB0_725:
	s_or_b64 exec, exec, s[68:69]
	s_movk_i32 s26, 0xfaff
	v_cmp_lt_i32_e32 vcc, s26, v129
	s_and_saveexec_b64 s[68:69], vcc
	s_xor_b64 s[68:69], exec, s[68:69]
	s_cbranch_execz .LBB0_729
	v_mov_b32_e32 v30, v29
	v_mov_b32_e32 v31, v29
	v_mov_b32_e32 v28, v29
	v_mov_b64_e32 v[98:99], v[30:31]
	v_cmp_gt_u32_e32 vcc, s33, v130
	v_mov_b64_e32 v[96:97], v[28:29]
	s_and_saveexec_b64 s[74:75], vcc
	s_cbranch_execz .LBB0_728
	v_lshlrev_b32_e32 v28, 4, v130
	global_load_dwordx4 v[96:99], v28, s[38:39] offset:-4096

.LBB0_732:
	v_mov_b32_e32 v30, v29
	v_mov_b32_e32 v31, v29
	v_mov_b32_e32 v28, v29
	v_mov_b64_e32 v[98:99], v[30:31]
	v_mov_b64_e32 v[96:97], v[28:29]

.LBB0_740:
	v_mov_b32_e32 v30, v29
	v_mov_b32_e32 v31, v29
	v_mov_b32_e32 v28, v29
	v_mov_b64_e32 v[102:103], v[30:31]
	v_mov_b64_e32 v[100:101], v[28:29]
.LBB0_741:
	s_or_b64 exec, exec, s[68:69]
	s_add_u32 s0, s38, 0x20000
	s_addc_u32 s1, s39, 0
.LBB0_742:
	v_lshlrev_b32_e32 v30, 7, v188
	v_ashrrev_i32_e32 v31, 31, v30
	v_lshl_add_u64 v[30:31], v[30:31], 1, s[0:1]
	v_lshlrev_b32_e32 v28, 3, v189
	v_lshl_add_u64 v[30:31], v[30:31], 0, v[28:29]
	global_load_dwordx2 v[178:179], v[30:31], off
	global_load_dwordx2 v[180:181], v[30:31], off offset:32
	global_load_dwordx2 v[182:183], v[30:31], off offset:64
	global_load_dwordx2 v[184:185], v[30:31], off offset:96
	global_load_dwordx2 v[186:187], v[30:31], off offset:128
	global_load_dwordx2 v[176:177], v[30:31], off offset:160
	global_load_dwordx2 v[174:175], v[30:31], off offset:192
	s_nop 0
	global_load_dwordx2 v[30:31], v[30:31], off offset:224
.LBB0_743:
	v_lshrrev_b32_e32 v28, 3, v128
	v_mad_u32_u24 v191, v128, s15, 0
	v_xor_b32_e32 v104, v189, v28
	v_lshl_add_u32 v104, v104, 4, v191
	ds_read_b128 v[104:107], v104
	v_mul_lo_u32 v108, v188, s15
	v_add3_u32 v116, 0, v108, v114
	ds_read_b128 v[132:135], v116 offset:34816
	v_bitop3_b32 v108, v189, v28, 4 bitop3:0x36
	v_lshl_add_u32 v108, v108, 4, v191
	ds_read_b128 v[108:111], v108
	ds_read_b128 v[140:143], v116 offset:34880
	v_bitop3_b32 v112, v189, v28, 8 bitop3:0x36
	s_waitcnt lgkmcnt(2)
	v_mfma_f32_16x16x32_bf16 v[104:107], v[104:107], v[132:135], 0
	v_lshl_add_u32 v112, v112, 4, v191
	ds_read_b128 v[112:115], v112
	ds_read_b128 v[144:147], v116 offset:34944
	v_or_b32_e32 v120, 4, v28
	s_waitcnt lgkmcnt(2)
	v_mfma_f32_16x16x32_bf16 v[104:107], v[108:111], v[140:143], v[104:107]
	v_bitop3_b32 v108, v189, v28, 12 bitop3:0x36
	v_lshl_add_u32 v108, v108, 4, v191
	ds_read_b128 v[108:111], v108
	ds_read_b128 v[136:139], v116 offset:35008
	s_waitcnt lgkmcnt(2)
	v_mfma_f32_16x16x32_bf16 v[104:107], v[112:115], v[144:147], v[104:107]
	v_bitop3_b32 v112, v28, v189, 2 bitop3:0x36
	v_or_b32_e32 v116, 2, v28
	v_or_b32_e32 v124, 6, v28
	v_or_b32_e32 v128, 8, v28
	s_waitcnt lgkmcnt(0)
	v_mfma_f32_16x16x32_bf16 v[104:107], v[108:111], v[136:139], v[104:107]
	v_lshl_add_u32 v108, v112, 4, v191
	ds_read_b128 v[108:111], v108 offset:4352
	v_bitop3_b32 v112, v189, v116, 4 bitop3:0x36
	v_lshl_add_u32 v112, v112, 4, v191
	ds_read_b128 v[112:115], v112 offset:4352
	v_or_b32_e32 v192, 10, v28
	v_or_b32_e32 v196, 12, v28
	s_waitcnt lgkmcnt(1)
	v_mfma_f32_16x16x32_bf16 v[108:111], v[108:111], v[132:135], 0
	s_andn2_b64 vcc, exec, s[16:17]
	v_and_b32_e32 v197, 0xffff0000, v170
	v_lshlrev_b32_e32 v198, 16, v171
	s_waitcnt lgkmcnt(0)
	v_mfma_f32_16x16x32_bf16 v[108:111], v[112:115], v[140:143], v[108:111]
	v_bitop3_b32 v112, v189, v116, 8 bitop3:0x36
	v_lshl_add_u32 v112, v112, 4, v191
	ds_read_b128 v[112:115], v112 offset:4352
	v_and_b32_e32 v199, 0xffff0000, v171
	v_and_b32_e32 v171, 0xffff0000, v163
	s_waitcnt lgkmcnt(0)
	v_mfma_f32_16x16x32_bf16 v[108:111], v[112:115], v[144:147], v[108:111]
	v_bitop3_b32 v112, v189, v116, 12 bitop3:0x36
	v_lshl_add_u32 v112, v112, 4, v191
	ds_read_b128 v[112:115], v112 offset:4352
	v_bitop3_b32 v116, v189, v28, 4 bitop3:0x14
	v_lshl_add_u32 v116, v116, 4, v191
	ds_read_b128 v[116:119], v116 offset:8704
	s_waitcnt lgkmcnt(1)
	v_mfma_f32_16x16x32_bf16 v[108:111], v[112:115], v[136:139], v[108:111]
	v_bitop3_b32 v112, v28, v189, 4 bitop3:0x36
	v_lshl_add_u32 v112, v112, 4, v191
	ds_read_b128 v[112:115], v112 offset:8704
	s_waitcnt lgkmcnt(0)
	v_mfma_f32_16x16x32_bf16 v[112:115], v[112:115], v[132:135], 0
	v_mfma_f32_16x16x32_bf16 v[112:115], v[116:119], v[140:143], v[112:115]
	v_bitop3_b32 v116, v189, v120, 8 bitop3:0x36
	v_lshl_add_u32 v116, v116, 4, v191
	ds_read_b128 v[116:119], v116 offset:8704
	s_waitcnt lgkmcnt(0)
	v_mfma_f32_16x16x32_bf16 v[112:115], v[116:119], v[144:147], v[112:115]
	v_bitop3_b32 v116, v189, v120, 12 bitop3:0x36
	v_lshl_add_u32 v116, v116, 4, v191
	ds_read_b128 v[116:119], v116 offset:8704
	v_bitop3_b32 v120, v189, v124, 4 bitop3:0x36
	v_lshl_add_u32 v120, v120, 4, v191
	ds_read_b128 v[120:123], v120 offset:13056
	s_waitcnt lgkmcnt(1)
	v_mfma_f32_16x16x32_bf16 v[112:115], v[116:119], v[136:139], v[112:115]
	v_bitop3_b32 v116, v28, v189, 6 bitop3:0x36
	v_lshl_add_u32 v116, v116, 4, v191
	ds_read_b128 v[116:119], v116 offset:13056
	s_waitcnt lgkmcnt(0)
	v_mfma_f32_16x16x32_bf16 v[116:119], v[116:119], v[132:135], 0
	v_mfma_f32_16x16x32_bf16 v[116:119], v[120:123], v[140:143], v[116:119]
	v_bitop3_b32 v120, v189, v124, 8 bitop3:0x36
	v_lshl_add_u32 v120, v120, 4, v191
	ds_read_b128 v[120:123], v120 offset:13056
	s_waitcnt lgkmcnt(0)
	v_mfma_f32_16x16x32_bf16 v[116:119], v[120:123], v[144:147], v[116:119]
	v_bitop3_b32 v120, v189, v124, 12 bitop3:0x36
	v_lshl_add_u32 v120, v120, 4, v191
	ds_read_b128 v[120:123], v120 offset:13056
	v_bitop3_b32 v124, v189, v128, 4 bitop3:0x36
	v_lshl_add_u32 v124, v124, 4, v191
	ds_read_b128 v[124:127], v124 offset:17408
	s_waitcnt lgkmcnt(1)
	v_mfma_f32_16x16x32_bf16 v[116:119], v[120:123], v[136:139], v[116:119]
	v_bitop3_b32 v120, v28, v189, 8 bitop3:0x36
	v_lshl_add_u32 v120, v120, 4, v191
	ds_read_b128 v[120:123], v120 offset:17408
	s_waitcnt lgkmcnt(0)
	v_mfma_f32_16x16x32_bf16 v[120:123], v[120:123], v[132:135], 0
	v_mfma_f32_16x16x32_bf16 v[120:123], v[124:127], v[140:143], v[120:123]
	v_bitop3_b32 v124, v189, v28, 8 bitop3:0x14
	v_lshl_add_u32 v124, v124, 4, v191
	ds_read_b128 v[124:127], v124 offset:17408
	s_waitcnt lgkmcnt(0)
	v_mfma_f32_16x16x32_bf16 v[120:123], v[124:127], v[144:147], v[120:123]
	v_bitop3_b32 v124, v189, v128, 12 bitop3:0x36
	v_lshl_add_u32 v124, v124, 4, v191
	ds_read_b128 v[124:127], v124 offset:17408
	v_bitop3_b32 v128, v189, v192, 4 bitop3:0x36
	v_lshl_add_u32 v128, v128, 4, v191
	ds_read_b128 v[128:131], v128 offset:21760
	s_waitcnt lgkmcnt(1)
	v_mfma_f32_16x16x32_bf16 v[120:123], v[124:127], v[136:139], v[120:123]
	v_bitop3_b32 v124, v28, v189, 10 bitop3:0x36
	v_lshl_add_u32 v124, v124, 4, v191
	ds_read_b128 v[124:127], v124 offset:21760
	s_waitcnt lgkmcnt(0)
	v_mfma_f32_16x16x32_bf16 v[124:127], v[124:127], v[132:135], 0
	v_mfma_f32_16x16x32_bf16 v[124:127], v[128:131], v[140:143], v[124:127]
	v_bitop3_b32 v128, v189, v192, 8 bitop3:0x36
	v_lshl_add_u32 v128, v128, 4, v191
	ds_read_b128 v[128:131], v128 offset:21760
	s_waitcnt lgkmcnt(0)
	v_mfma_f32_16x16x32_bf16 v[124:127], v[128:131], v[144:147], v[124:127]
	v_bitop3_b32 v128, v189, v192, 12 bitop3:0x36
	v_lshl_add_u32 v128, v128, 4, v191
	ds_read_b128 v[128:131], v128 offset:21760
	v_bitop3_b32 v192, v189, v196, 4 bitop3:0x36
	v_lshl_add_u32 v192, v192, 4, v191
	ds_read_b128 v[192:195], v192 offset:26112
	s_waitcnt lgkmcnt(1)
	v_mfma_f32_16x16x32_bf16 v[124:127], v[128:131], v[136:139], v[124:127]
	v_bitop3_b32 v128, v28, v189, 12 bitop3:0x36
	v_lshl_add_u32 v128, v128, 4, v191
	ds_read_b128 v[128:131], v128 offset:26112
	s_waitcnt lgkmcnt(0)
	v_mfma_f32_16x16x32_bf16 v[128:131], v[128:131], v[132:135], 0
	v_mfma_f32_16x16x32_bf16 v[128:131], v[192:195], v[140:143], v[128:131]
	v_bitop3_b32 v192, v189, v196, 8 bitop3:0x36
	v_lshl_add_u32 v192, v192, 4, v191
	ds_read_b128 v[192:195], v192 offset:26112
	v_lshlrev_b32_e32 v196, 16, v170
	s_waitcnt lgkmcnt(0)
	v_mfma_f32_16x16x32_bf16 v[128:131], v[192:195], v[144:147], v[128:131]
	v_bitop3_b32 v192, v189, v28, 12 bitop3:0x14
	v_lshl_add_u32 v192, v192, 4, v191
	ds_read_b128 v[192:195], v192 offset:26112
	v_lshlrev_b32_e32 v170, 16, v163
	s_waitcnt lgkmcnt(0)
	v_mfma_f32_16x16x32_bf16 v[128:131], v[192:195], v[136:139], v[128:131]
	v_bitop3_b32 v192, v28, v189, 14 bitop3:0x36
	v_lshl_add_u32 v192, v192, 4, v191
	ds_read_b128 v[192:195], v192 offset:30464
	v_or_b32_e32 v28, 14, v28
	s_waitcnt lgkmcnt(0)
	v_mfma_f32_16x16x32_bf16 v[132:135], v[192:195], v[132:135], 0
	v_bitop3_b32 v192, v189, v28, 4 bitop3:0x36
	v_lshl_add_u32 v192, v192, 4, v191
	ds_read_b128 v[192:195], v192 offset:30464
	v_and_b32_e32 v163, 0xffff0000, v158
	s_waitcnt lgkmcnt(0)
	v_mfma_f32_16x16x32_bf16 v[132:135], v[192:195], v[140:143], v[132:135]
	v_bitop3_b32 v140, v189, v28, 8 bitop3:0x36
	v_lshl_add_u32 v140, v140, 4, v191
	ds_read_b128 v[140:143], v140 offset:30464
	v_bitop3_b32 v28, v189, v28, 12 bitop3:0x36
	v_lshl_add_u32 v28, v28, 4, v191
	s_waitcnt lgkmcnt(0)
	v_mfma_f32_16x16x32_bf16 v[132:135], v[140:143], v[144:147], v[132:135]
	ds_read_b128 v[140:143], v28 offset:30464
	v_lshl_add_u32 v144, s84, 7, v188
	v_ashrrev_i32_e32 v145, 31, v144
	s_waitcnt lgkmcnt(0)
	v_mfma_f32_16x16x32_bf16 v[132:135], v[140:143], v[136:139], v[132:135]
	v_lshlrev_b64 v[200:201], 11, v[144:145]
	v_or_b32_e32 v28, s8, v190
	v_lshl_add_u64 v[136:137], s[2:3], 0, v[200:201]
	v_lshlrev_b32_e32 v192, 16, v168
	v_and_b32_e32 v193, 0xffff0000, v168
	v_lshlrev_b32_e32 v194, 16, v169
	v_and_b32_e32 v195, 0xffff0000, v169
	v_lshlrev_b32_e32 v188, 16, v166
	v_and_b32_e32 v189, 0xffff0000, v166
	v_lshlrev_b32_e32 v190, 16, v167
	v_and_b32_e32 v191, 0xffff0000, v167
	v_lshlrev_b32_e32 v168, 16, v162
	v_and_b32_e32 v169, 0xffff0000, v162
	v_lshlrev_b32_e32 v162, 16, v158
	v_lshlrev_b32_e32 v166, 16, v159
	v_and_b32_e32 v167, 0xffff0000, v159
	v_lshlrev_b32_e32 v146, 16, v164
	v_and_b32_e32 v147, 0xffff0000, v164
	v_lshlrev_b32_e32 v158, 16, v165
	v_and_b32_e32 v159, 0xffff0000, v165
	v_lshlrev_b32_e32 v142, 16, v160
	v_and_b32_e32 v143, 0xffff0000, v160
	v_lshlrev_b32_e32 v144, 16, v161
	v_and_b32_e32 v145, 0xffff0000, v161
	v_lshlrev_b32_e32 v138, 16, v156
	v_and_b32_e32 v139, 0xffff0000, v156
	v_lshlrev_b32_e32 v140, 16, v157
	v_and_b32_e32 v141, 0xffff0000, v157
	s_cbranch_vccnz .LBB0_745
	v_lshl_add_u64 v[160:161], s[2:3], 0, v[200:201]
	s_waitcnt vmcnt(0)
	v_pk_add_f32 v[200:201], v[172:173], v[104:105] op_sel_hi:[0,1]
	s_mov_b64 s[0:1], 0x400
	v_pk_add_f32 v[164:165], v[172:173], v[106:107] op_sel_hi:[0,1]
	v_pk_mul_f32 v[200:201], v[200:201], v[196:197]
	v_lshl_add_u64 v[156:157], v[160:161], 0, s[0:1]
	v_pk_mul_f32 v[164:165], v[164:165], v[198:199]
	v_cvt_pk_bf16_f32 v200, v200, v201
	v_lshl_add_u64 v[160:161], v[28:29], 1, v[160:161]
	v_cvt_pk_bf16_f32 v201, v164, v165
	global_store_dwordx2 v[160:161], v[200:201], off offset:1024
	v_pk_add_f32 v[200:201], v[172:173], v[108:109] op_sel_hi:[0,1]
	v_pk_add_f32 v[164:165], v[172:173], v[110:111] op_sel_hi:[0,1]
	v_pk_mul_f32 v[200:201], v[200:201], v[192:193]
	v_pk_mul_f32 v[164:165], v[164:165], v[194:195]
	v_cvt_pk_bf16_f32 v200, v200, v201
	s_nop 0
	v_cvt_pk_bf16_f32 v201, v164, v165
	global_store_dwordx2 v[160:161], v[200:201], off offset:1056
	v_pk_add_f32 v[200:201], v[172:173], v[112:113] op_sel_hi:[0,1]
	v_pk_add_f32 v[164:165], v[172:173], v[114:115] op_sel_hi:[0,1]
	v_pk_mul_f32 v[200:201], v[200:201], v[188:189]
	v_pk_mul_f32 v[164:165], v[164:165], v[190:191]
	v_cvt_pk_bf16_f32 v200, v200, v201
	s_nop 0
	v_cvt_pk_bf16_f32 v201, v164, v165
	global_store_dwordx2 v[160:161], v[200:201], off offset:1088
	v_pk_add_f32 v[200:201], v[172:173], v[116:117] op_sel_hi:[0,1]
	v_pk_add_f32 v[164:165], v[172:173], v[118:119] op_sel_hi:[0,1]
	v_pk_mul_f32 v[200:201], v[200:201], v[168:169]
	v_pk_mul_f32 v[164:165], v[164:165], v[170:171]
	v_cvt_pk_bf16_f32 v200, v200, v201
	s_nop 0
	v_cvt_pk_bf16_f32 v201, v164, v165
	global_store_dwordx2 v[160:161], v[200:201], off offset:1120
	v_pk_add_f32 v[200:201], v[172:173], v[120:121] op_sel_hi:[0,1]
	v_pk_add_f32 v[164:165], v[172:173], v[122:123] op_sel_hi:[0,1]
	v_pk_mul_f32 v[200:201], v[200:201], v[162:163]
	v_pk_mul_f32 v[164:165], v[164:165], v[166:167]
	v_cvt_pk_bf16_f32 v200, v200, v201
	s_nop 0
	v_cvt_pk_bf16_f32 v201, v164, v165
	global_store_dwordx2 v[160:161], v[200:201], off offset:1152
	v_pk_add_f32 v[200:201], v[172:173], v[124:125] op_sel_hi:[0,1]
	v_pk_add_f32 v[164:165], v[172:173], v[126:127] op_sel_hi:[0,1]
	v_pk_mul_f32 v[200:201], v[200:201], v[146:147]
	v_pk_mul_f32 v[164:165], v[164:165], v[158:159]
	v_cvt_pk_bf16_f32 v200, v200, v201
	s_nop 0
	v_cvt_pk_bf16_f32 v201, v164, v165
	global_store_dwordx2 v[160:161], v[200:201], off offset:1184
	v_pk_add_f32 v[164:165], v[172:173], v[130:131] op_sel_hi:[0,1]
	v_pk_add_f32 v[200:201], v[172:173], v[128:129] op_sel_hi:[0,1]
	v_pk_mul_f32 v[164:165], v[164:165], v[144:145]
	v_pk_mul_f32 v[200:201], v[200:201], v[142:143]
	s_nop 0
	v_cvt_pk_bf16_f32 v200, v200, v201
	v_cvt_pk_bf16_f32 v201, v164, v165
	global_store_dwordx2 v[160:161], v[200:201], off offset:1216
	v_pk_add_f32 v[160:161], v[172:173], v[134:135] op_sel_hi:[0,1]
	v_pk_add_f32 v[164:165], v[172:173], v[132:133] op_sel_hi:[0,1]
	v_pk_mul_f32 v[200:201], v[160:161], v[140:141]
	v_pk_mul_f32 v[160:161], v[164:165], v[138:139]
	s_nop 0
	v_cvt_pk_bf16_f32 v160, v160, v161
	v_cvt_pk_bf16_f32 v161, v200, v201
	s_cbranch_execnz .LBB0_655
	s_branch .LBB0_654

	.amdhsa_kernel _Z10fwd_kernel4Args
		.amdhsa_group_segment_fixed_size 0
		.amdhsa_private_segment_fixed_size 0
		.amdhsa_kernarg_size 432
		.amdhsa_user_sgpr_count 2
		.amdhsa_user_sgpr_dispatch_ptr 0
		.amdhsa_user_sgpr_queue_ptr 0
		.amdhsa_user_sgpr_kernarg_segment_ptr 1
		.amdhsa_user_sgpr_dispatch_id 0
		.amdhsa_user_sgpr_kernarg_preload_length 0
		.amdhsa_user_sgpr_kernarg_preload_offset 0
		.amdhsa_user_sgpr_private_segment_size 0
		.amdhsa_uses_dynamic_stack 0
		.amdhsa_enable_private_segment 0
		.amdhsa_system_sgpr_workgroup_id_x 1
		.amdhsa_system_sgpr_workgroup_id_y 0
		.amdhsa_system_sgpr_workgroup_id_z 0
		.amdhsa_system_sgpr_workgroup_info 0
		.amdhsa_system_vgpr_workitem_id 2
		.amdhsa_next_free_vgpr 235
		.amdhsa_next_free_sgpr 102
		.amdhsa_accum_offset 236
		.amdhsa_reserve_vcc 1
		.amdhsa_float_round_mode_32 0
		.amdhsa_float_round_mode_16_64 0
		.amdhsa_float_denorm_mode_32 3
		.amdhsa_float_denorm_mode_16_64 3
		.amdhsa_dx10_clamp 1
		.amdhsa_ieee_mode 1
		.amdhsa_fp16_overflow 0
		.amdhsa_tg_split 0
		.amdhsa_exception_fp_ieee_invalid_op 0
		.amdhsa_exception_fp_denorm_src 0
		.amdhsa_exception_fp_ieee_div_zero 0
		.amdhsa_exception_fp_ieee_overflow 0
		.amdhsa_exception_fp_ieee_underflow 0
		.amdhsa_exception_fp_ieee_inexact 0
		.amdhsa_exception_int_div_zero 0
	.end_amdhsa_kernel

amdhsa.kernels:
  - .agpr_count:     0
    .args:
      - .offset:         0
        .size:           176
        .value_kind:     by_value
      - .offset:         176
        .size:           4
        .value_kind:     hidden_block_count_x
      - .offset:         180
        .size:           4
        .value_kind:     hidden_block_count_y
      - .offset:         184
        .size:           4
        .value_kind:     hidden_block_count_z
      - .offset:         188
        .size:           2
        .value_kind:     hidden_group_size_x
      - .offset:         190
        .size:           2
        .value_kind:     hidden_group_size_y
      - .offset:         192
        .size:           2
        .value_kind:     hidden_group_size_z
      - .offset:         194
        .size:           2
        .value_kind:     hidden_remainder_x
      - .offset:         196
        .size:           2
        .value_kind:     hidden_remainder_y
      - .offset:         198
        .size:           2
        .value_kind:     hidden_remainder_z
      - .offset:         216
        .size:           8
        .value_kind:     hidden_global_offset_x
      - .offset:         224
        .size:           8
        .value_kind:     hidden_global_offset_y
      - .offset:         232
        .size:           8
        .value_kind:     hidden_global_offset_z
      - .offset:         240
        .size:           2
        .value_kind:     hidden_grid_dims
      - .offset:         264
        .size:           8
        .value_kind:     hidden_multigrid_sync_arg
      - .offset:         296
        .size:           4
        .value_kind:     hidden_dynamic_lds_size
    .group_segment_fixed_size: 0
    .kernarg_segment_align: 8
    .kernarg_segment_size: 432
    .language:       OpenCL C
    .language_version:
      - 2
      - 0
    .max_flat_workgroup_size: 512
    .name:           _Z10fwd_kernel4Args
    .private_segment_fixed_size: 0
    .sgpr_count:     108
    .sgpr_spill_count: 51
    .symbol:         _Z10fwd_kernel4Args.kd
    .uniform_work_group_size: 1
    .uses_dynamic_stack: false
    .vgpr_count:     235
    .vgpr_spill_count: 0
    .wavefront_size: 64
